# prompt-attention unit prologue: dead normalisation arithmetic of the first three staged K chunks removed (9 ds_bpermute round trips per unit)
# baseline (speedup 1.0000x reference)
.LBB0_857:
	s_or_b64 exec, exec, s[4:5]
	v_xor_b32_e32 v17, 1, v1
	v_cmp_lt_i32_e32 vcc, v17, v242
	s_nop 1
	v_cndmask_b32_e32 v17, v1, v17, vcc
	v_lshlrev_b32_e32 v196, 2, v17
	v_xor_b32_e32 v49, 2, v1
	v_cmp_lt_i32_e32 vcc, v49, v242
	s_nop 1
	v_cndmask_b32_e32 v49, v1, v49, vcc
	v_lshlrev_b32_e32 v197, 2, v49
	v_xor_b32_e32 v49, 4, v1
	v_cmp_lt_i32_e32 vcc, v49, v242
	s_nop 1
	v_cndmask_b32_e32 v49, v1, v49, vcc
	v_lshlrev_b32_e32 v198, 2, v49
	s_waitcnt vmcnt(0)
	v_lshlrev_b32_e32 v20, 2, v166
	v_and_b32_e32 v20, 12, v20
	v_bfe_u32 v21, v166, 2, 2
	v_bitop3_b32 v20, v20, v45, v21 bitop3:0x36
	v_lshlrev_b32_e32 v199, 8, v166
	v_lshlrev_b32_e32 v201, 4, v20
	v_add3_u32 v20, 0, v201, v199
	ds_write_b128 v20, v[116:119]
	v_lshlrev_b32_e32 v17, 2, v168
	v_and_b32_e32 v17, 12, v17
	v_bfe_u32 v22, v168, 2, 2
	v_bitop3_b32 v17, v17, v45, v22 bitop3:0x36
	v_lshlrev_b32_e32 v202, 8, v168
	v_lshlrev_b32_e32 v203, 4, v17
	v_add3_u32 v17, 0, v203, v202
	ds_write_b128 v17, v[120:123]
	v_lshlrev_b32_e32 v20, 2, v170
	v_and_b32_e32 v20, 12, v20
	v_bfe_u32 v21, v170, 2, 2
	v_bitop3_b32 v20, v20, v45, v21 bitop3:0x36
	v_lshlrev_b32_e32 v204, 8, v170
	v_lshlrev_b32_e32 v205, 4, v20
	v_add3_u32 v20, 0, v205, v204
	ds_write_b128 v20, v[124:127]
	v_and_b32_e32 v17, 0xffff0000, v128
	v_lshlrev_b32_e32 v16, 16, v128
	v_pk_mul_f32 v[24:25], v[16:17], v[16:17]
	v_and_b32_e32 v19, 0xffff0000, v129
	v_lshlrev_b32_e32 v18, 16, v129
	v_pk_mul_f32 v[52:53], v[18:19], v[18:19]
	v_add_f32_e32 v24, v24, v25
	v_and_b32_e32 v21, 0xffff0000, v130
	v_lshlrev_b32_e32 v20, 16, v130
	v_add_f32_e32 v24, v52, v24
	v_pk_mul_f32 v[56:57], v[20:21], v[20:21]
	v_add_f32_e32 v24, v53, v24
	v_and_b32_e32 v23, 0xffff0000, v131
	v_lshlrev_b32_e32 v22, 16, v131
	v_add_f32_e32 v24, v56, v24
	v_pk_mul_f32 v[64:65], v[22:23], v[22:23]
	v_add_f32_e32 v24, v57, v24
	v_add_f32_e32 v24, v64, v24
	v_add_f32_e32 v24, v65, v24
	ds_bpermute_b32 v25, v196, v24
	s_sub_i32 s21, 0, s8
	s_lshl_b32 s12, s9, 7
	s_waitcnt lgkmcnt(0)
	v_add_f32_e32 v24, v24, v25
	ds_bpermute_b32 v25, v197, v24
	s_waitcnt lgkmcnt(0)
	v_add_f32_e32 v25, v24, v25
	ds_bpermute_b32 v26, v198, v25
	v_mov_b32_e32 v24, 1.0
	s_and_saveexec_b64 s[4:5], s[0:1]
	s_cbranch_execz .LBB0_865
	s_waitcnt lgkmcnt(0)
	v_add_f32_e32 v24, v25, v26
	v_fmamk_f32 v24, v24, 0x3c800000, v160
	v_mul_f32_e32 v25, 0x4b800000, v24
	v_cmp_gt_f32_e32 vcc, s10, v24
	s_nop 1
	v_cndmask_b32_e32 v24, v24, v25, vcc
	v_rsq_f32_e32 v24, v24
	s_nop 0
	v_mul_f32_e32 v25, 0x45800000, v24
	v_cndmask_b32_e32 v24, v24, v25, vcc
